# SEAM3 without the XCD L2 write-back: every P2/P3 product that P4 reads is stored write-through (S5 table stores now sc1 too)
# baseline (speedup 1.0000x reference)
; __device__ __forceinline__ double d_exp(double x) {
;     const double k = __builtin_rint(x * 1.4426950408889634);
;     const double r = (x - k * 0.6931471803691238) - k * 1.9082149292705877e-10;
;     double p = 1.0 / 6227020800.0;
;     p = p * r + 1.0 / 479001600.0; p = p * r + 1.0 / 39916800.0; p = p * r + 1.0 / 3628800.0; p = p * r + 1.0 / 362880.0; p = p * r + 1.0 / 40320.0;
;     p = p * r + 1.0 / 5040.0; p = p * r + 1.0 / 720.0; p = p * r + 1.0 / 120.0; p = p * r + 1.0 / 24.0; p = p * r + 1.0 / 6.0; p = p * r + 0.5; p = p * r + 1.0; p = p * r + 1.0;
;     const long long bits = ((long long)k + 1023ll) << 52;
;     return p * __longlong_as_double(bits);
; }
; __device__ __forceinline__ void d_sincos(double th, double& s, double& c) {
;     const double n = __builtin_rint(th * 0.63661977236758134);
;     const double y = (th - n * 1.57079632673412561417) - n * 6.07710050650619224932e-11;
;     const double z = y * y;
;     double ps = -1.0 / 1307674368000.0; ps = ps * z + 1.0 / 6227020800.0; ps = ps * z - 1.0 / 39916800.0; ps = ps * z + 1.0 / 362880.0; ps = ps * z - 1.0 / 5040.0; ps = ps * z + 1.0 / 120.0; ps = ps * z - 1.0 / 6.0;
;     const double sy = y + y * z * ps;
;     double pc = 1.0 / 20922789888000.0; pc = pc * z - 1.0 / 87178291200.0; pc = pc * z + 1.0 / 479001600.0; pc = pc * z - 1.0 / 3628800.0; pc = pc * z + 1.0 / 40320.0; pc = pc * z - 1.0 / 720.0; pc = pc * z + 1.0 / 24.0; pc = pc * z - 0.5;
;     const double cy = 1.0 + z * pc;
;     const int q = (int)((long long)n & 3ll);
;     s = (q == 0) ? sy : (q == 1) ? cy : (q == 2) ? -sy : -cy;
;     c = (q == 0) ? cy : (q == 1) ? -sy : (q == 2) ? -cy : sy;
; __device__ __forceinline__ void s5_consts_pair(const Args& a, int i) {
;     ...
;     double s, c; d_sincos(dt * aim, s, c); const double mag = d_exp(dt * are), abr = mag * c, abi = mag * s;
;     ABAR[2 * i] = (float)abr; ABAR[2 * i + 1] = (float)abi;
;     { double s2, c2; d_sincos(16.0 * dt * aim, s2, c2); const double m2 = d_exp(16.0 * dt * are); A16[2 * i] = (float)(m2 * c2); A16[2 * i + 1] = (float)(m2 * s2); }
.LBB0_282:
	s_or_b64 exec, exec, s[26:27]
	v_cvt_f64_f32_e32 v[134:135], v148
	v_mul_f64 v[158:159], v[142:143], v[134:135]
	v_mul_f64 v[148:149], v[158:159], s[8:9]
	v_rndne_f64_e32 v[166:167], v[148:149]
	v_fmac_f64_e32 v[158:159], s[10:11], v[166:167]
	v_fmac_f64_e32 v[158:159], s[14:15], v[166:167]
	v_mov_b32_e32 v156, 0xeff8d898
	v_mov_b32_e32 v157, 0x3e21eed8
	v_fma_f64 v[148:149], s[24:25], v[158:159], v[156:157]
	v_fmac_f64_e32 v[138:139], v[158:159], v[148:149]
	v_fmac_f64_e32 v[140:141], v[158:159], v[138:139]
	v_mov_b32_e32 v160, 0xa556c734
	v_mov_b32_e32 v161, 0x3ec71de3
	v_mov_b32_e32 v149, 0x3efa01a0
	v_mov_b32_e32 v148, v144
	v_fma_f64 v[138:139], v[158:159], v[140:141], v[160:161]
	v_mov_b64_e32 v[140:141], v[148:149]
	v_fmac_f64_e32 v[140:141], v[158:159], v[138:139]
	v_fmac_f64_e32 v[144:145], v[158:159], v[140:141]
	v_fmac_f64_e32 v[146:147], v[158:159], v[144:145]
	v_mov_b32_e32 v164, 0x11111111
	v_mov_b32_e32 v165, 0x3f811111
	v_mov_b32_e32 v145, 0x3fa55555
	v_mov_b32_e32 v144, v150
	v_fma_f64 v[138:139], v[158:159], v[146:147], v[164:165]
	v_mov_b64_e32 v[140:141], v[144:145]
	v_fmac_f64_e32 v[140:141], v[158:159], v[138:139]
	v_fmac_f64_e32 v[150:151], v[158:159], v[140:141]
	v_ldexp_f64 v[140:141], v[166:167], s1
	v_floor_f64_e32 v[140:141], v[140:141]
	v_fma_f64 v[138:139], v[158:159], v[150:151], 0.5
	v_fmac_f64_e32 v[166:167], 0xc1f00000, v[140:141]
	v_fma_f64 v[138:139], v[158:159], v[138:139], 1.0
	v_cvt_u32_f64_e32 v137, v[166:167]
	v_mov_b32_e32 v140, 0x3ff00000
	v_fma_f64 v[138:139], v[158:159], v[138:139], 1.0
	v_lshl_add_u32 v137, v137, 20, v140
	v_mul_f64 v[140:141], v[138:139], v[136:137]
	v_lshlrev_b32_e32 v136, 1, v132
	v_ashrrev_i32_e32 v137, 31, v136
	v_lshl_add_u64 v[146:147], v[136:137], 2, s[94:95]
	v_mul_f64 v[138:139], v[140:141], v[152:153]
	v_mul_f64 v[140:141], v[140:141], v[154:155]
	v_add_co_u32_e32 v152, vcc, 0x2300000, v146
	v_cvt_f32_f64_e32 v151, v[138:139]
	v_cvt_f32_f64_e32 v150, v[140:141]
	v_addc_co_u32_e32 v153, vcc, 0, v147, vcc
	v_ldexp_f64 v[154:155], v[142:143], 4
	s_mov_b32 s8, 0x6dc9c883
	global_store_dwordx2 v[152:153], v[150:151], off sc1
	v_mul_f64 v[150:151], v[154:155], v[130:131]
	s_mov_b32 s9, 0x3fe45f30
	v_mul_f64 v[152:153], v[150:151], s[8:9]
	s_mov_b32 s8, 0x54400000
	v_rndne_f64_e32 v[166:167], v[152:153]
	s_mov_b32 s9, 0xbff921fb
	v_fmac_f64_e32 v[150:151], s[8:9], v[166:167]
	s_mov_b32 s8, 0x1a626331
	s_mov_b32 s9, 0xbdd0b461
	v_fmac_f64_e32 v[150:151], s[8:9], v[166:167]
	v_mul_f64 v[168:169], v[150:151], v[150:151]
	v_mov_b32_e32 v158, 0x13a86d09
	v_mov_b32_e32 v159, 0x3de61246
	s_mov_b32 s11, 0xbd6ae7f3
	s_mov_b32 s10, 0xe733b81f
	v_mov_b32_e32 v152, 0x67f544e4
	v_mov_b32_e32 v153, 0xbe5ae645
	v_fmac_f64_e32 v[158:159], s[10:11], v[168:169]
	v_mov_b64_e32 v[170:171], v[152:153]
	v_fmac_f64_e32 v[170:171], v[168:169], v[158:159]
	v_mov_b32_e32 v158, 0xa8c07c9d
	v_mov_b32_e32 v159, 0xbda93974
	s_mov_b32 s11, 0x3d2ae7f3
	v_fmac_f64_e32 v[158:159], s[10:11], v[168:169]
	v_fmac_f64_e32 v[156:157], v[168:169], v[158:159]
	v_mov_b32_e32 v158, 0xb7789f5c
	v_mov_b32_e32 v159, 0xbe927e4f
	v_mov_b64_e32 v[172:173], v[158:159]
	v_mov_b32_e32 v148, 0x1a01a01a
	v_fmac_f64_e32 v[172:173], v[168:169], v[156:157]
	v_mov_b64_e32 v[174:175], v[148:149]
	v_mov_b32_e32 v156, 0x16c16c17
	v_mov_b32_e32 v157, 0xbf56c16c
	v_fmac_f64_e32 v[174:175], v[168:169], v[172:173]
	v_mov_b64_e32 v[172:173], v[156:157]
	v_mov_b32_e32 v149, 0xbf2a01a0
	v_fmac_f64_e32 v[160:161], v[168:169], v[170:171]
	v_fmac_f64_e32 v[172:173], v[168:169], v[174:175]
	v_mov_b64_e32 v[174:175], v[148:149]
	v_mov_b32_e32 v144, 0x55555555
	v_fmac_f64_e32 v[174:175], v[168:169], v[160:161]
	v_mov_b64_e32 v[160:161], v[144:145]
	v_mov_b32_e32 v145, 0xbfc55555
	v_fmac_f64_e32 v[164:165], v[168:169], v[174:175]
	v_fmac_f64_e32 v[160:161], v[168:169], v[172:173]
	v_mov_b64_e32 v[172:173], v[144:145]
	v_fmac_f64_e32 v[172:173], v[168:169], v[164:165]
	v_ldexp_f64 v[164:165], v[166:167], s1
	v_floor_f64_e32 v[164:165], v[164:165]
	v_fmac_f64_e32 v[166:167], 0xc1f00000, v[164:165]
	v_cvt_u32_f64_e32 v137, v[166:167]
	s_mov_b32 s8, 0x13a86d09
	v_mul_f64 v[170:171], v[150:151], v[168:169]
	v_fma_f64 v[160:161], v[168:169], v[160:161], -0.5
	v_and_b32_e32 v137, 3, v137
	s_mov_b32 s9, 0x3de61246
	v_fmac_f64_e32 v[150:151], v[170:171], v[172:173]
	v_fma_f64 v[160:161], v[168:169], v[160:161], 1.0
	v_cmp_lt_i32_e32 vcc, 0, v137
	s_and_saveexec_b64 s[10:11], vcc
	s_cbranch_execz .LBB0_288
	v_cmp_ne_u32_e32 vcc, 1, v137
	v_xor_b32_e32 v165, 0x80000000, v151
	v_mov_b32_e32 v164, v150
	s_and_saveexec_b64 s[14:15], vcc
	s_xor_b64 s[14:15], exec, s[14:15]
	v_cmp_eq_u32_e32 vcc, 2, v137
	v_xor_b32_e32 v137, 0x80000000, v161
	s_nop 0
	v_cndmask_b32_e32 v166, v160, v150, vcc
	v_cndmask_b32_e64 v167, -v161, -v151, vcc
	v_cndmask_b32_e32 v165, v151, v137, vcc
	v_cndmask_b32_e32 v164, v150, v160, vcc
	v_mov_b64_e32 v[150:151], v[166:167]
	s_andn2_saveexec_b64 s[14:15], s[14:15]
	v_mov_b64_e32 v[150:151], v[160:161]
	s_or_b64 exec, exec, s[14:15]
	v_mov_b64_e32 v[160:161], v[164:165]
; __device__ __forceinline__ double d_exp(double x) {
;     const double k = __builtin_rint(x * 1.4426950408889634);
;     const double r = (x - k * 0.6931471803691238) - k * 1.9082149292705877e-10;
;     double p = 1.0 / 6227020800.0;
;     p = p * r + 1.0 / 479001600.0; p = p * r + 1.0 / 39916800.0; p = p * r + 1.0 / 3628800.0; p = p * r + 1.0 / 362880.0; p = p * r + 1.0 / 40320.0;
;     p = p * r + 1.0 / 5040.0; p = p * r + 1.0 / 720.0; p = p * r + 1.0 / 120.0; p = p * r + 1.0 / 24.0; p = p * r + 1.0 / 6.0; p = p * r + 0.5; p = p * r + 1.0; p = p * r + 1.0;
;     const long long bits = ((long long)k + 1023ll) << 52;
;     return p * __longlong_as_double(bits);
; }
; __device__ __forceinline__ void d_sincos(double th, double& s, double& c) {
;     const double n = __builtin_rint(th * 0.63661977236758134);
;     const double y = (th - n * 1.57079632673412561417) - n * 6.07710050650619224932e-11;
;     const double z = y * y;
;     double ps = -1.0 / 1307674368000.0; ps = ps * z + 1.0 / 6227020800.0; ps = ps * z - 1.0 / 39916800.0; ps = ps * z + 1.0 / 362880.0; ps = ps * z - 1.0 / 5040.0; ps = ps * z + 1.0 / 120.0; ps = ps * z - 1.0 / 6.0;
;     const double sy = y + y * z * ps;
;     double pc = 1.0 / 20922789888000.0; pc = pc * z - 1.0 / 87178291200.0; pc = pc * z + 1.0 / 479001600.0; pc = pc * z - 1.0 / 3628800.0; pc = pc * z + 1.0 / 40320.0; pc = pc * z - 1.0 / 720.0; pc = pc * z + 1.0 / 24.0; pc = pc * z - 0.5;
;     const double cy = 1.0 + z * pc;
;     const int q = (int)((long long)n & 3ll);
;     s = (q == 0) ? sy : (q == 1) ? cy : (q == 2) ? -sy : -cy;
;     c = (q == 0) ? cy : (q == 1) ? -sy : (q == 2) ? -cy : sy;
; __device__ __forceinline__ void s5_consts_pair(const Args& a, int i) {
;     ...
;     { double s2, c2; d_sincos(16.0 * dt * aim, s2, c2); const double m2 = d_exp(16.0 * dt * are); A16[2 * i] = (float)(m2 * c2); A16[2 * i + 1] = (float)(m2 * s2); }
;     { double s2, c2; d_sincos(256.0 * dt * aim, s2, c2); const double m2 = d_exp(256.0 * dt * are); A256[2 * i] = (float)(m2 * c2); A256[2 * i + 1] = (float)(m2 * s2); }
.LBB0_288:
	s_or_b64 exec, exec, s[10:11]
	s_mov_b32 s10, 0x652b82fe
	v_mul_f64 v[166:167], v[154:155], v[134:135]
	s_mov_b32 s11, 0x3ff71547
	v_mul_f64 v[154:155], v[166:167], s[10:11]
	s_mov_b32 s10, 0xfee00000
	v_rndne_f64_e32 v[168:169], v[154:155]
	s_mov_b32 s11, 0xbfe62e42
	v_fmac_f64_e32 v[166:167], s[10:11], v[168:169]
	s_mov_b32 s10, 0x35793c76
	s_mov_b32 s11, 0xbdea39ef
	v_fmac_f64_e32 v[166:167], s[10:11], v[168:169]
	v_mov_b32_e32 v154, 0xeff8d898
	v_mov_b32_e32 v155, 0x3e21eed8
	v_fma_f64 v[164:165], s[8:9], v[166:167], v[154:155]
	v_mov_b32_e32 v153, 0x3e5ae645
	v_fmac_f64_e32 v[152:153], v[166:167], v[164:165]
	v_mov_b32_e32 v159, 0x3e927e4f
	v_fmac_f64_e32 v[158:159], v[166:167], v[152:153]
	v_mov_b32_e32 v164, 0xa556c734
	v_mov_b32_e32 v165, 0x3ec71de3
	v_mov_b32_e32 v149, 0x3efa01a0
	v_fma_f64 v[152:153], v[166:167], v[158:159], v[164:165]
	v_mov_b64_e32 v[158:159], v[148:149]
	v_fmac_f64_e32 v[158:159], v[166:167], v[152:153]
	v_mov_b32_e32 v153, 0x3f2a01a0
	v_mov_b32_e32 v152, v148
	v_fmac_f64_e32 v[152:153], v[166:167], v[158:159]
	v_mov_b32_e32 v157, 0x3f56c16c
	v_fmac_f64_e32 v[156:157], v[166:167], v[152:153]
	v_mov_b32_e32 v158, 0x11111111
	v_mov_b32_e32 v159, 0x3f811111
	v_mov_b32_e32 v145, 0x3fa55555
	v_fma_f64 v[152:153], v[166:167], v[156:157], v[158:159]
	v_mov_b64_e32 v[156:157], v[144:145]
	v_fmac_f64_e32 v[156:157], v[166:167], v[152:153]
	v_mov_b32_e32 v153, 0x3fc55555
	v_mov_b32_e32 v152, v144
	v_fmac_f64_e32 v[152:153], v[166:167], v[156:157]
	v_ldexp_f64 v[156:157], v[168:169], s1
	v_floor_f64_e32 v[156:157], v[156:157]
	v_fma_f64 v[152:153], v[166:167], v[152:153], 0.5
	v_fmac_f64_e32 v[168:169], 0xc1f00000, v[156:157]
	v_fma_f64 v[152:153], v[166:167], v[152:153], 1.0
	v_cvt_u32_f64_e32 v137, v[168:169]
	v_mov_b32_e32 v144, 0x3ff00000
	v_fma_f64 v[152:153], v[166:167], v[152:153], 1.0
	v_lshl_add_u32 v157, v137, 20, v144
	v_mov_b32_e32 v156, 0
	v_mul_f64 v[152:153], v[152:153], v[156:157]
	v_mul_f64 v[156:157], v[152:153], v[160:161]
	v_mul_f64 v[150:151], v[152:153], v[150:151]
	v_add_co_u32_e32 v152, vcc, 0x2308000, v146
	v_cvt_f32_f64_e32 v151, v[150:151]
	v_cvt_f32_f64_e32 v150, v[156:157]
	v_addc_co_u32_e32 v153, vcc, 0, v147, vcc
	global_store_dwordx2 v[152:153], v[150:151], off sc1
	v_ldexp_f64 v[152:153], v[142:143], 8
	s_mov_b32 s8, 0x6dc9c883
	v_mul_f64 v[142:143], v[152:153], v[130:131]
	s_mov_b32 s9, 0x3fe45f30
	v_mul_f64 v[150:151], v[142:143], s[8:9]
	s_mov_b32 s8, 0x54400000
	v_rndne_f64_e32 v[160:161], v[150:151]
	s_mov_b32 s9, 0xbff921fb
	v_fmac_f64_e32 v[142:143], s[8:9], v[160:161]
	s_mov_b32 s8, 0x1a626331
	s_mov_b32 s9, 0xbdd0b461
	v_fmac_f64_e32 v[142:143], s[8:9], v[160:161]
	v_mul_f64 v[166:167], v[142:143], v[142:143]
	v_mov_b32_e32 v156, 0x13a86d09
	v_mov_b32_e32 v157, 0x3de61246
	s_mov_b32 s11, 0xbd6ae7f3
	s_mov_b32 s10, 0xe733b81f
	v_mov_b32_e32 v150, 0x67f544e4
	v_mov_b32_e32 v151, 0xbe5ae645
	v_fmac_f64_e32 v[156:157], s[10:11], v[166:167]
	v_mov_b64_e32 v[168:169], v[150:151]
	v_fmac_f64_e32 v[168:169], v[166:167], v[156:157]
	v_mov_b32_e32 v156, 0xa8c07c9d
	v_mov_b32_e32 v157, 0xbda93974
	s_mov_b32 s11, 0x3d2ae7f3
	v_fmac_f64_e32 v[156:157], s[10:11], v[166:167]
	v_fmac_f64_e32 v[154:155], v[166:167], v[156:157]
	v_mov_b32_e32 v156, 0xb7789f5c
	v_mov_b32_e32 v157, 0xbe927e4f
	v_mov_b64_e32 v[170:171], v[156:157]
	v_mov_b32_e32 v148, 0x1a01a01a
	v_fmac_f64_e32 v[170:171], v[166:167], v[154:155]
	v_mov_b64_e32 v[172:173], v[148:149]
	v_mov_b32_e32 v154, 0x16c16c17
	v_mov_b32_e32 v155, 0xbf56c16c
	v_fmac_f64_e32 v[172:173], v[166:167], v[170:171]
	v_mov_b64_e32 v[170:171], v[154:155]
	v_mov_b32_e32 v149, 0xbf2a01a0
	v_fmac_f64_e32 v[164:165], v[166:167], v[168:169]
	v_fmac_f64_e32 v[170:171], v[166:167], v[172:173]
	v_mov_b64_e32 v[172:173], v[148:149]
	v_mov_b32_e32 v144, 0x55555555
	v_fmac_f64_e32 v[172:173], v[166:167], v[164:165]
	v_mov_b64_e32 v[164:165], v[144:145]
	v_fmac_f64_e32 v[164:165], v[166:167], v[170:171]
	v_mov_b32_e32 v145, 0xbfc55555
	v_fmac_f64_e32 v[158:159], v[166:167], v[172:173]
	v_fma_f64 v[164:165], v[166:167], v[164:165], -0.5
	v_mov_b64_e32 v[170:171], v[144:145]
	v_fmac_f64_e32 v[170:171], v[166:167], v[158:159]
	v_fma_f64 v[158:159], v[166:167], v[164:165], 1.0
	v_ldexp_f64 v[164:165], v[160:161], s1
	v_floor_f64_e32 v[164:165], v[164:165]
	v_fmac_f64_e32 v[160:161], 0xc1f00000, v[164:165]
	v_cvt_u32_f64_e32 v137, v[160:161]
	s_mov_b32 s8, 0x13a86d09
	v_mul_f64 v[168:169], v[142:143], v[166:167]
	v_and_b32_e32 v137, 3, v137
	s_mov_b32 s9, 0x3de61246
	v_fmac_f64_e32 v[142:143], v[168:169], v[170:171]
	v_cmp_lt_i32_e32 vcc, 0, v137
	s_and_saveexec_b64 s[10:11], vcc
	s_cbranch_execz .LBB0_294
	v_cmp_ne_u32_e32 vcc, 1, v137
	v_xor_b32_e32 v161, 0x80000000, v143
	v_mov_b32_e32 v160, v142
	s_and_saveexec_b64 s[14:15], vcc
	s_xor_b64 s[14:15], exec, s[14:15]
	v_cmp_eq_u32_e32 vcc, 2, v137
	v_xor_b32_e32 v137, 0x80000000, v159
	s_nop 0
	v_cndmask_b32_e32 v164, v158, v142, vcc
	v_cndmask_b32_e64 v165, -v159, -v143, vcc
	v_cndmask_b32_e32 v161, v143, v137, vcc
	v_cndmask_b32_e32 v160, v142, v158, vcc
	v_mov_b64_e32 v[142:143], v[164:165]
	s_andn2_saveexec_b64 s[14:15], s[14:15]
	v_mov_b64_e32 v[142:143], v[158:159]
	s_or_b64 exec, exec, s[14:15]
	v_mov_b64_e32 v[158:159], v[160:161]
; __device__ __forceinline__ void s5_consts_pair(const Args& a, int i) {
;     ...
;     { double s2, c2; d_sincos(256.0 * dt * aim, s2, c2); const double m2 = d_exp(256.0 * dt * are); A256[2 * i] = (float)(m2 * c2); A256[2 * i + 1] = (float)(m2 * s2); }
;     const double nr = abr - 1.0, ni = abi, den = are * are + aim * aim, cr = (nr * are + ni * aim) / den, ci = (ni * are - nr * aim) / den;
;     const float* br = a.in[I_BRE] + (size_t)i * 16; const float* bi = a.in[I_BIM] + (size_t)i * 16;
;     bf16* o_re = BBAR + (((size_t)g * 8 + 2 * (p >> 4)) * 16 + (p & 15)) * 16; bf16* o_im = o_re + 256;
; #pragma unroll
;     for (int ch = 0; ch < 16; ch += 2) { const double b0r = br[ch], b0i = bi[ch], b1r = br[ch + 1], b1i = bi[ch + 1];
.LBB0_294:
	s_or_b64 exec, exec, s[10:11]
	s_mov_b32 s10, 0x652b82fe
	v_mul_f64 v[152:153], v[152:153], v[134:135]
	s_mov_b32 s11, 0x3ff71547
	v_mul_f64 v[160:161], v[152:153], s[10:11]
	s_mov_b32 s10, 0xfee00000
	v_rndne_f64_e32 v[160:161], v[160:161]
	s_mov_b32 s11, 0xbfe62e42
	v_fmac_f64_e32 v[152:153], s[10:11], v[160:161]
	s_mov_b32 s10, 0x35793c76
	s_mov_b32 s11, 0xbdea39ef
	v_fmac_f64_e32 v[152:153], s[10:11], v[160:161]
	v_mov_b32_e32 v164, 0xeff8d898
	v_mov_b32_e32 v165, 0x3e21eed8
	v_fmac_f64_e32 v[164:165], s[8:9], v[152:153]
	v_mov_b32_e32 v151, 0x3e5ae645
	v_fmac_f64_e32 v[150:151], v[152:153], v[164:165]
	v_mov_b32_e32 v157, 0x3e927e4f
	v_fmac_f64_e32 v[156:157], v[152:153], v[150:151]
	v_mov_b32_e32 v150, 0xa556c734
	v_mov_b32_e32 v151, 0x3ec71de3
	v_mov_b32_e32 v149, 0x3efa01a0
	v_fmac_f64_e32 v[150:151], v[152:153], v[156:157]
	v_mov_b64_e32 v[156:157], v[148:149]
	v_fmac_f64_e32 v[156:157], v[152:153], v[150:151]
	v_mov_b32_e32 v149, 0x3f2a01a0
	v_fmac_f64_e32 v[148:149], v[152:153], v[156:157]
	v_mov_b32_e32 v155, 0x3f56c16c
	v_fmac_f64_e32 v[154:155], v[152:153], v[148:149]
	v_mov_b32_e32 v148, 0x11111111
	v_mov_b32_e32 v149, 0x3f811111
	v_mov_b32_e32 v145, 0x3fa55555
	v_fmac_f64_e32 v[148:149], v[152:153], v[154:155]
	v_mov_b64_e32 v[150:151], v[144:145]
	v_fmac_f64_e32 v[150:151], v[152:153], v[148:149]
	v_mov_b32_e32 v145, 0x3fc55555
	v_ldexp_f64 v[148:149], v[160:161], s1
	v_fmac_f64_e32 v[144:145], v[152:153], v[150:151]
	v_floor_f64_e32 v[148:149], v[148:149]
	v_fma_f64 v[144:145], v[152:153], v[144:145], 0.5
	v_fmac_f64_e32 v[160:161], 0xc1f00000, v[148:149]
	v_fma_f64 v[144:145], v[152:153], v[144:145], 1.0
	v_cvt_u32_f64_e32 v137, v[160:161]
	v_mov_b32_e32 v148, 0x3ff00000
	v_fma_f64 v[144:145], v[152:153], v[144:145], 1.0
	v_lshl_add_u32 v149, v137, 20, v148
	v_mov_b32_e32 v148, 0
	v_readlane_b32 s36, v249, 1
	v_mul_f64 v[144:145], v[144:145], v[148:149]
	v_lshlrev_b64 v[132:133], 6, v[132:133]
	v_readlane_b32 s38, v249, 3
	v_readlane_b32 s39, v249, 4
	v_readlane_b32 s40, v249, 5
	v_readlane_b32 s41, v249, 6
	v_mul_f64 v[148:149], v[144:145], v[158:159]
	s_mov_b32 s1, 0x2310000
	v_lshl_add_u64 v[158:159], s[38:39], 0, v[132:133]
	v_lshl_add_u64 v[160:161], s[40:41], 0, v[132:133]
	v_add_f64 v[132:133], v[140:141], -1.0
	v_mul_f64 v[142:143], v[144:145], v[142:143]
	v_add_co_u32_e32 v144, vcc, s1, v146
	v_mul_f64 v[140:141], v[130:131], v[130:131]
	v_mul_f64 v[164:165], v[132:133], v[134:135]
	v_cvt_f32_f64_e32 v143, v[142:143]
	v_cvt_f32_f64_e32 v142, v[148:149]
	v_addc_co_u32_e32 v145, vcc, 0, v147, vcc
	v_fmac_f64_e32 v[140:141], v[134:135], v[134:135]
	v_fmac_f64_e32 v[164:165], v[138:139], v[130:131]
	global_store_dwordx2 v[144:145], v[142:143], off sc1
	v_div_scale_f64 v[166:167], s[8:9], v[140:141], v[140:141], v[164:165]
	global_load_dwordx4 v[146:149], v[160:161], off
	v_rcp_f64_e32 v[168:169], v[166:167]
	global_load_dwordx4 v[142:145], v[158:159], off
	v_mul_f64 v[130:131], v[132:133], v[130:131]
	v_fma_f64 v[130:131], v[138:139], v[134:135], -v[130:131]
	v_fma_f64 v[170:171], -v[166:167], v[168:169], 1.0
	v_fmac_f64_e32 v[168:169], v[168:169], v[170:171]
	v_fma_f64 v[170:171], -v[166:167], v[168:169], 1.0
	v_div_scale_f64 v[132:133], s[8:9], v[140:141], v[140:141], v[130:131]
	global_load_dwordx4 v[150:153], v[158:159], off offset:16
	global_load_dwordx4 v[154:157], v[160:161], off offset:16
	v_fmac_f64_e32 v[168:169], v[168:169], v[170:171]
	v_div_scale_f64 v[170:171], vcc, v[164:165], v[140:141], v[164:165]
	v_rcp_f64_e32 v[134:135], v[132:133]
	v_mul_f64 v[172:173], v[170:171], v[168:169]
	v_fma_f64 v[166:167], -v[166:167], v[172:173], v[170:171]
	s_nop 0
	v_div_fmas_f64 v[138:139], v[166:167], v[168:169], v[172:173]
	v_div_fixup_f64 v[164:165], v[138:139], v[140:141], v[164:165]
	v_fma_f64 v[138:139], -v[132:133], v[134:135], 1.0
	v_fmac_f64_e32 v[134:135], v[134:135], v[138:139]
	v_fma_f64 v[138:139], -v[132:133], v[134:135], 1.0
	v_fmac_f64_e32 v[134:135], v[134:135], v[138:139]
	v_div_scale_f64 v[138:139], vcc, v[130:131], v[140:141], v[130:131]
	v_mul_f64 v[166:167], v[138:139], v[134:135]
	v_fma_f64 v[132:133], -v[132:133], v[166:167], v[138:139]
	s_lshl_b64 s[6:7], s[6:7], 7
	s_nop 0
	v_div_fmas_f64 v[132:133], v[132:133], v[134:135], v[166:167]
	v_div_fixup_f64 v[166:167], v[132:133], v[140:141], v[130:131]
	v_and_b32_e32 v130, 0x60, v136
	v_and_b32_e32 v131, 15, v0
	v_or3_b32 v130, s6, v130, v131
	v_mov_b32_e32 v131, s7
	v_lshlrev_b64 v[130:131], 5, v[130:131]
	v_lshl_add_u64 v[168:169], s[94:95], 0, v[130:131]
	global_load_dwordx4 v[130:133], v[158:159], off offset:48
	global_load_dwordx4 v[134:137], v[158:159], off offset:32
	global_load_dwordx4 v[138:141], v[160:161], off offset:48
	s_nop 0
	global_load_dwordx4 v[158:161], v[160:161], off offset:32
	s_mov_b64 s[6:7], 0x2320000
	s_mov_b32 s1, 0x2320000
	v_lshl_add_u64 v[170:171], v[168:169], 0, s[6:7]
	v_add_co_u32_e32 v168, vcc, s1, v168
	v_readlane_b32 s37, v249, 2
	s_nop 0
	v_addc_co_u32_e32 v169, vcc, 0, v169, vcc
	v_readlane_b32 s42, v249, 7
	v_readlane_b32 s43, v249, 8
	v_readlane_b32 s44, v249, 9
	v_readlane_b32 s45, v249, 10
	v_readlane_b32 s46, v249, 11
	v_readlane_b32 s47, v249, 12
	v_readlane_b32 s48, v249, 13
	v_readlane_b32 s49, v249, 14
	v_readlane_b32 s50, v249, 15
	v_readlane_b32 s51, v249, 16
	s_waitcnt vmcnt(7)
	v_cvt_f64_f32_e32 v[176:177], v146
	v_cvt_f64_f32_e32 v[146:147], v147
	s_waitcnt vmcnt(6)
; __device__ __forceinline__ unsigned pk2(float lo, float hi) { return pg8::cvt_pk_bf16(lo, hi); }
; __device__ __forceinline__ void s5_consts_pair(const Args& a, int i) {
;     ...
;     for (int ch = 0; ch < 16; ch += 2) { const double b0r = br[ch], b0i = bi[ch], b1r = br[ch + 1], b1i = bi[ch + 1];
;         *(unsigned*)(o_re + ch) = pk2((float)(cr * b0r - ci * b0i), (float)(cr * b1r - ci * b1i));
;         *(unsigned*)(o_im + ch) = pk2((float)(cr * b0i + ci * b0r), (float)(cr * b1i + ci * b1r)); }
	v_cvt_f64_f32_e32 v[172:173], v143
	v_cvt_f64_f32_e32 v[174:175], v142
	v_mul_f64 v[142:143], v[166:167], v[146:147]
	v_mul_f64 v[178:179], v[166:167], v[176:177]
	v_fma_f64 v[178:179], v[164:165], v[174:175], -v[178:179]
	v_fma_f64 v[142:143], v[164:165], v[172:173], -v[142:143]
	v_mul_f64 v[176:177], v[164:165], v[176:177]
	v_cvt_f32_f64_e32 v142, v[142:143]
	v_cvt_f32_f64_e32 v143, v[178:179]
	v_fmac_f64_e32 v[176:177], v[166:167], v[174:175]
	v_mul_f64 v[146:147], v[164:165], v[146:147]
	v_cvt_f64_f32_e32 v[174:175], v148
	v_cvt_f64_f32_e32 v[148:149], v149
	v_cvt_pk_bf16_f32 v142, v143, v142
	v_cvt_f32_f64_e32 v143, v[176:177]
	v_fmac_f64_e32 v[146:147], v[166:167], v[172:173]
	v_cvt_f64_f32_e32 v[172:173], v145
	v_cvt_f64_f32_e32 v[144:145], v144
	v_mul_f64 v[176:177], v[166:167], v[148:149]
	v_mul_f64 v[178:179], v[166:167], v[174:175]
	v_mul_f64 v[174:175], v[164:165], v[174:175]
	v_cvt_f32_f64_e32 v146, v[146:147]
	v_fma_f64 v[178:179], v[164:165], v[144:145], -v[178:179]
	v_fma_f64 v[176:177], v[164:165], v[172:173], -v[176:177]
	v_fmac_f64_e32 v[174:175], v[166:167], v[144:145]
	v_mul_f64 v[144:145], v[164:165], v[148:149]
	v_cvt_pk_bf16_f32 v146, v143, v146
	v_cvt_f32_f64_e32 v143, v[176:177]
	v_cvt_f32_f64_e32 v147, v[178:179]
	v_fmac_f64_e32 v[144:145], v[166:167], v[172:173]
	v_cvt_pk_bf16_f32 v143, v147, v143
	v_cvt_f32_f64_e32 v147, v[174:175]
	v_cvt_f32_f64_e32 v144, v[144:145]
	s_waitcnt vmcnt(4)
	v_cvt_f64_f32_e32 v[172:173], v154
	v_cvt_f64_f32_e32 v[154:155], v155
	v_cvt_pk_bf16_f32 v147, v147, v144
	v_cvt_f64_f32_e32 v[148:149], v151
	v_cvt_f64_f32_e32 v[150:151], v150
	v_mul_f64 v[144:145], v[166:167], v[154:155]
	v_mul_f64 v[174:175], v[166:167], v[172:173]
	v_mul_f64 v[172:173], v[164:165], v[172:173]
	v_fma_f64 v[174:175], v[164:165], v[150:151], -v[174:175]
	v_fma_f64 v[144:145], v[164:165], v[148:149], -v[144:145]
	v_fmac_f64_e32 v[172:173], v[166:167], v[150:151]
	v_mul_f64 v[150:151], v[164:165], v[154:155]
	v_cvt_f32_f64_e32 v144, v[144:145]
	v_cvt_f32_f64_e32 v145, v[174:175]
	v_fmac_f64_e32 v[150:151], v[166:167], v[148:149]
	v_cvt_f64_f32_e32 v[154:155], v156
	v_cvt_f64_f32_e32 v[156:157], v157
	v_cvt_pk_bf16_f32 v144, v145, v144
	v_cvt_f32_f64_e32 v145, v[172:173]
	v_cvt_f32_f64_e32 v148, v[150:151]
	v_cvt_f64_f32_e32 v[150:151], v153
	v_cvt_f64_f32_e32 v[152:153], v152
	v_mul_f64 v[172:173], v[166:167], v[156:157]
	v_mul_f64 v[174:175], v[166:167], v[154:155]
	v_fma_f64 v[174:175], v[164:165], v[152:153], -v[174:175]
	v_fma_f64 v[172:173], v[164:165], v[150:151], -v[172:173]
	v_cvt_pk_bf16_f32 v148, v145, v148
	v_cvt_f32_f64_e32 v145, v[172:173]
	v_cvt_f32_f64_e32 v149, v[174:175]
	v_cvt_pk_bf16_f32 v145, v149, v145
	global_store_dwordx4 v[168:169], v[142:145], off sc1
	s_nop 1
	v_mul_f64 v[142:143], v[164:165], v[154:155]
	v_fmac_f64_e32 v[142:143], v[166:167], v[152:153]
	v_cvt_f32_f64_e32 v144, v[142:143]
	v_mul_f64 v[142:143], v[164:165], v[156:157]
	v_fmac_f64_e32 v[142:143], v[166:167], v[150:151]
	v_cvt_f32_f64_e32 v142, v[142:143]
	v_cvt_pk_bf16_f32 v149, v144, v142
	global_store_dwordx4 v[170:171], v[146:149], off offset:512 sc1
	s_waitcnt vmcnt(4)
	v_cvt_f64_f32_e32 v[142:143], v135
	v_cvt_f64_f32_e32 v[144:145], v134
	s_waitcnt vmcnt(2)
	v_cvt_f64_f32_e32 v[146:147], v158
	v_cvt_f64_f32_e32 v[148:149], v159
	v_mul_f64 v[134:135], v[166:167], v[148:149]
	v_mul_f64 v[150:151], v[166:167], v[146:147]
	v_fma_f64 v[150:151], v[164:165], v[144:145], -v[150:151]
	v_fma_f64 v[134:135], v[164:165], v[142:143], -v[134:135]
	v_mul_f64 v[146:147], v[164:165], v[146:147]
	v_cvt_f32_f64_e32 v134, v[134:135]
	v_cvt_f32_f64_e32 v135, v[150:151]
	v_fmac_f64_e32 v[146:147], v[166:167], v[144:145]
	v_mul_f64 v[144:145], v[164:165], v[148:149]
	v_cvt_pk_bf16_f32 v134, v135, v134
	v_cvt_f32_f64_e32 v135, v[146:147]
	v_fmac_f64_e32 v[144:145], v[166:167], v[142:143]
	v_cvt_f64_f32_e32 v[146:147], v160
	v_cvt_f64_f32_e32 v[148:149], v161
	v_cvt_f32_f64_e32 v142, v[144:145]
	v_cvt_f64_f32_e32 v[144:145], v137
	v_cvt_f64_f32_e32 v[136:137], v136
	v_mul_f64 v[150:151], v[166:167], v[148:149]
	v_mul_f64 v[152:153], v[166:167], v[146:147]
	v_mul_f64 v[146:147], v[164:165], v[146:147]
	v_fma_f64 v[152:153], v[164:165], v[136:137], -v[152:153]
	v_fma_f64 v[150:151], v[164:165], v[144:145], -v[150:151]
	v_fmac_f64_e32 v[146:147], v[166:167], v[136:137]
	v_mul_f64 v[136:137], v[164:165], v[148:149]
	v_cvt_pk_bf16_f32 v142, v135, v142
	v_cvt_f32_f64_e32 v135, v[150:151]
	v_cvt_f32_f64_e32 v143, v[152:153]
	v_fmac_f64_e32 v[136:137], v[166:167], v[144:145]
	v_cvt_pk_bf16_f32 v135, v143, v135
	v_cvt_f32_f64_e32 v143, v[146:147]
	v_cvt_f32_f64_e32 v136, v[136:137]
	v_cvt_f64_f32_e32 v[146:147], v138
	v_cvt_f64_f32_e32 v[138:139], v139
	v_cvt_pk_bf16_f32 v143, v143, v136
	v_cvt_f64_f32_e32 v[144:145], v131
	v_cvt_f64_f32_e32 v[130:131], v130
	v_mul_f64 v[136:137], v[166:167], v[138:139]
	v_mul_f64 v[148:149], v[166:167], v[146:147]
	v_mul_f64 v[146:147], v[164:165], v[146:147]
	v_fma_f64 v[148:149], v[164:165], v[130:131], -v[148:149]
	v_fma_f64 v[136:137], v[164:165], v[144:145], -v[136:137]
	v_fmac_f64_e32 v[146:147], v[166:167], v[130:131]
	v_mul_f64 v[130:131], v[164:165], v[138:139]
	v_cvt_f32_f64_e32 v136, v[136:137]
	v_cvt_f32_f64_e32 v137, v[148:149]
	v_fmac_f64_e32 v[130:131], v[166:167], v[144:145]
	v_cvt_pk_bf16_f32 v136, v137, v136
	v_cvt_f32_f64_e32 v137, v[146:147]
	v_cvt_f32_f64_e32 v130, v[130:131]
	v_cvt_f64_f32_e32 v[138:139], v140
	v_cvt_f64_f32_e32 v[140:141], v141
	v_cvt_pk_bf16_f32 v144, v137, v130
	v_cvt_f64_f32_e32 v[130:131], v133
	v_cvt_f64_f32_e32 v[132:133], v132
	v_mul_f64 v[146:147], v[166:167], v[140:141]
	v_mul_f64 v[148:149], v[166:167], v[138:139]
	v_fma_f64 v[148:149], v[164:165], v[132:133], -v[148:149]
	v_fma_f64 v[146:147], v[164:165], v[130:131], -v[146:147]
	v_cvt_f32_f64_e32 v137, v[146:147]
	v_cvt_f32_f64_e32 v145, v[148:149]
	v_cvt_pk_bf16_f32 v137, v145, v137
	global_store_dwordx4 v[170:171], v[134:137], off offset:16 sc1
	s_nop 1
	v_mul_f64 v[134:135], v[164:165], v[138:139]
	v_fmac_f64_e32 v[134:135], v[166:167], v[132:133]
	v_mul_f64 v[132:133], v[164:165], v[140:141]
	v_fmac_f64_e32 v[132:133], v[166:167], v[130:131]
	v_cvt_f32_f64_e32 v134, v[134:135]
	v_cvt_f32_f64_e32 v130, v[132:133]
	v_cvt_pk_bf16_f32 v145, v134, v130
	global_store_dwordx4 v[170:171], v[142:145], off offset:528 sc1

; __device__ __forceinline__ unsigned xb_add(unsigned* p, unsigned v) { return __hip_atomic_fetch_add(p, v, __ATOMIC_RELAXED, __HIP_MEMORY_SCOPE_AGENT); }
; __device__ __forceinline__ void xcd_barrier(const XcdBarrier& b) {
;     ...
;         const unsigned old = xb_add(&bar[XB_XSUB(b.x)], 1u);
;         const unsigned gen = old / nloc;
;         if (old + 1u == (gen + 1u) * nloc) {
;             __builtin_amdgcn_fence(__ATOMIC_RELEASE, "agent");
;             asm volatile("s_waitcnt vmcnt(0)" ::: "memory");
;             const unsigned og = xb_add(&bar[XB_TOP], 1u);
;             const unsigned tg = og / nx;
;             if (og + 1u == (tg + 1u) * nx) xb_add(&bar[XB_TOPGEN], 1u);
.LBB0_925:
	s_andn2_saveexec_b64 s[0:1], s[8:9]
	s_cbranch_execz .LBB0_945
	s_mov_b64 s[10:11], exec
	s_waitcnt vmcnt(0) lgkmcnt(0)
	s_waitcnt vmcnt(0)
	v_mbcnt_lo_u32_b32 v3, s10, 0
	v_mbcnt_hi_u32_b32 v3, s11, v3
	v_cmp_eq_u32_e32 vcc, 0, v3
	s_and_saveexec_b64 s[8:9], vcc
	s_cbranch_execz .LBB0_928
	s_bcnt1_i32_b64 s2, s[10:11]
	s_getpc_b64 s[0:1]
	s_add_u32 s0, s0, g_ctl@rel32@lo+29700
	s_addc_u32 s1, s1, g_ctl@rel32@hi+29708
	v_mov_b32_e32 v4, 0
	v_mov_b32_e32 v5, s2
	global_atomic_add v4, v4, v5, s[0:1] sc0
